# plus EpiQKV row-scale loads and P0 row loads issued together (were serial round trips)
# baseline (speedup 1.0000x reference)
; #define GAS __attribute__((address_space(1)))
; __device__ __forceinline__ unsigned pk2(float lo, float hi) { unsigned r; asm("v_cvt_pk_bf16_f32 %0, %1, %2" : "=v"(r) : "v"(lo), "v"(hi)); return r; }
; #define IN(i) in_ptr(lds, (i))
; __device__ __forceinline__ void fix_row(float* hrow, bf16* hb, float* rout, int lane, const float* part, int nparts) {
;     f32x4 v[8]; float ss = 0.f;
; #pragma unroll
;     for (int j = 0; j < 8; ++j) v[j] = *(const f32x4*)(hrow + 4 * lane + 256 * j);
;     if (part != nullptr) {
;         for (int s = 0; s < nparts; ++s) {
; #pragma unroll
;             for (int j = 0; j < 8; ++j) v[j] = v[j] + *(const f32x4*)(part + (size_t)s * (256 * 2048) + 4 * lane + 256 * j); }
; #pragma unroll
;         for (int j = 0; j < 8; ++j) *(f32x4*)(hrow + 4 * lane + 256 * j) = v[j];
;     }
; #pragma unroll
;     for (int j = 0; j < 8; ++j) { ss += (v[j].x * v[j].x + v[j].y * v[j].y) + (v[j].z * v[j].z + v[j].w * v[j].w);
;         v2u w; w.x = pk2(v[j].x, v[j].y); w.y = pk2(v[j].z, v[j].w); *(v2u*)(hb + 4 * lane + 256 * j) = w; }
;     ss = wave_sum(ss, lane);
;     if (lane == 0) *rout = __builtin_amdgcn_rsqf(ss * (1.0f / D) + EPS);
; __global__ void __launch_bounds__(NWAVES * 64, 2) fwd(Args a) {
;     ...
;         for (int row = gw; row < M; row += NGW) { const int b = row >= LP ? 1 : 0, t = row - b * LP; float* hr = H + (size_t)row * D;
;             gfp src = t >= 128 ? IN(I_X) + (size_t)(b * SEQ + t - 128) * D : IN(I_META) + (size_t)(t >= PADR ? t - PADR : 0) * D;
; #pragma unroll
;             for (int j = 0; j < 8; ++j) { f32x4 v = *(const GAS f32x4*)(src + 4 * lane + 256 * j); if (t < PADR) v = (f32x4){0.f, 0.f, 0.f, 0.f}; *(f32x4*)(hr + 4 * lane + 256 * j) = v; }
;             fix_row(hr, HN + (size_t)row * D, RS + row, lane, nullptr, 0); }
.LBB0_20:
	s_lshl_b64 s[16:17], s[8:9], 13
	s_add_u32 s18, s18, s16
	s_addc_u32 s19, s19, s17
	s_nop 1
	global_load_dwordx4 v[10:13], v0, s[18:19]
	v_lshl_add_u64 v[18:19], s[0:1], 0, v[2:3]
	s_cmpk_lt_i32 s30, 0x70
	v_add_co_u32_e32 v42, vcc, s28, v18
	s_cselect_b64 s[16:17], -1, 0
	s_nop 0
	v_addc_co_u32_e32 v43, vcc, 0, v19, vcc
	v_add_co_u32_e32 v26, vcc, s26, v18
	v_lshl_add_u64 v[28:29], s[18:19], 0, v[0:1]
	s_nop 0
	v_addc_co_u32_e32 v27, vcc, 0, v19, vcc
	v_add_co_u32_e32 v38, vcc, s27, v28
	v_lshl_add_u64 v[44:45], s[0:1], 0, v[4:5]
	s_nop 0
	v_addc_co_u32_e32 v39, vcc, 0, v29, vcc
	v_add_co_u32_e32 v44, vcc, s29, v44
	global_load_dwordx4 v[60:63], v0, s[18:19] offset:1024
	global_load_dwordx4 v[64:67], v0, s[18:19] offset:2048
	global_load_dwordx4 v[68:71], v0, s[18:19] offset:3072
	global_load_dwordx4 v[72:75], v[38:39], off
	global_load_dwordx4 v[76:79], v[38:39], off offset:1024
	global_load_dwordx4 v[80:83], v[38:39], off offset:2048
	global_load_dwordx4 v[84:87], v[38:39], off offset:3072
	s_waitcnt vmcnt(7)
	v_cndmask_b32_e64 v13, v13, 0, s[16:17]
	v_cndmask_b32_e64 v12, v12, 0, s[16:17]
	v_cndmask_b32_e64 v11, v11, 0, s[16:17]
	v_cndmask_b32_e64 v10, v10, 0, s[16:17]
	global_store_dwordx4 v[42:43], v[10:13], off offset:-4096
	v_mul_f32_e32 v49, v13, v13
	v_mul_f32_e32 v48, v11, v11
	v_cvt_pk_bf16_f32 v46, v10, v11
	v_cvt_pk_bf16_f32 v47, v12, v13
	v_fmac_f32_e32 v49, v12, v12
	v_fmac_f32_e32 v48, v10, v10
	v_add_f32_e32 v10, v48, v49
	v_addc_co_u32_e32 v45, vcc, 0, v45, vcc
	s_waitcnt vmcnt(7)
	v_cndmask_b32_e64 v17, v63, 0, s[16:17]
	v_cndmask_b32_e64 v16, v62, 0, s[16:17]
	v_cndmask_b32_e64 v15, v61, 0, s[16:17]
	v_cndmask_b32_e64 v14, v60, 0, s[16:17]
	global_store_dwordx4 v[26:27], v[14:17], off offset:1024
	v_mul_f32_e32 v11, v15, v15
	v_mul_f32_e32 v12, v17, v17
	v_fmac_f32_e32 v11, v14, v14
	v_fmac_f32_e32 v12, v16, v16
	v_add_f32_e32 v11, v11, v12
	v_add_f32_e32 v10, v10, v11
	v_cvt_pk_bf16_f32 v49, v16, v17
	v_cvt_pk_bf16_f32 v48, v14, v15
	s_waitcnt vmcnt(7)
	v_cndmask_b32_e64 v21, v67, 0, s[16:17]
	v_cndmask_b32_e64 v20, v66, 0, s[16:17]
	v_cndmask_b32_e64 v19, v65, 0, s[16:17]
	v_cndmask_b32_e64 v18, v64, 0, s[16:17]
	global_store_dwordx4 v[26:27], v[18:21], off offset:2048
	v_mul_f32_e32 v11, v19, v19
	v_mul_f32_e32 v12, v21, v21
	v_fmac_f32_e32 v11, v18, v18
	v_fmac_f32_e32 v12, v20, v20
	v_add_f32_e32 v11, v11, v12
	v_add_f32_e32 v10, v10, v11
	v_cvt_pk_bf16_f32 v14, v18, v19
	v_cvt_pk_bf16_f32 v15, v20, v21
	s_waitcnt vmcnt(7)
	v_cndmask_b32_e64 v25, v71, 0, s[16:17]
	v_cndmask_b32_e64 v24, v70, 0, s[16:17]
	v_cndmask_b32_e64 v23, v69, 0, s[16:17]
	v_cndmask_b32_e64 v22, v68, 0, s[16:17]
	global_store_dwordx4 v[26:27], v[22:25], off offset:3072
	v_mul_f32_e32 v11, v23, v23
	v_mul_f32_e32 v12, v25, v25
	v_fmac_f32_e32 v11, v22, v22
	v_fmac_f32_e32 v12, v24, v24
	v_add_f32_e32 v11, v11, v12
	v_add_f32_e32 v10, v10, v11
	v_cvt_pk_bf16_f32 v16, v22, v23
	v_cvt_pk_bf16_f32 v17, v24, v25
	s_waitcnt vmcnt(7)
	v_cndmask_b32_e64 v29, v75, 0, s[16:17]
	v_cndmask_b32_e64 v28, v74, 0, s[16:17]
	v_cndmask_b32_e64 v27, v73, 0, s[16:17]
	v_cndmask_b32_e64 v26, v72, 0, s[16:17]
	global_store_dwordx4 v[42:43], v[26:29], off
	v_mul_f32_e32 v11, v27, v27
	v_mul_f32_e32 v12, v29, v29
	v_fmac_f32_e32 v11, v26, v26
	v_fmac_f32_e32 v12, v28, v28
	v_add_f32_e32 v11, v11, v12
	v_add_f32_e32 v10, v10, v11
	v_cvt_pk_bf16_f32 v18, v26, v27
	v_cvt_pk_bf16_f32 v19, v28, v29
	s_waitcnt vmcnt(7)
	v_cndmask_b32_e64 v33, v79, 0, s[16:17]
	v_cndmask_b32_e64 v32, v78, 0, s[16:17]
	v_cndmask_b32_e64 v31, v77, 0, s[16:17]
	v_cndmask_b32_e64 v30, v76, 0, s[16:17]
	global_store_dwordx4 v[42:43], v[30:33], off offset:1024
	v_mul_f32_e32 v11, v31, v31
	v_mul_f32_e32 v12, v33, v33
	v_fmac_f32_e32 v11, v30, v30
	v_fmac_f32_e32 v12, v32, v32
	v_add_f32_e32 v11, v11, v12
	v_add_f32_e32 v10, v10, v11
	v_cvt_pk_bf16_f32 v20, v30, v31
	v_cvt_pk_bf16_f32 v21, v32, v33
	s_waitcnt vmcnt(7)
	v_cndmask_b32_e64 v37, v83, 0, s[16:17]
	v_cndmask_b32_e64 v36, v82, 0, s[16:17]
	v_cndmask_b32_e64 v35, v81, 0, s[16:17]
	v_cndmask_b32_e64 v34, v80, 0, s[16:17]
	global_store_dwordx4 v[42:43], v[34:37], off offset:2048
	v_mul_f32_e32 v11, v35, v35
	v_mul_f32_e32 v12, v37, v37
	v_fmac_f32_e32 v11, v34, v34
	v_fmac_f32_e32 v12, v36, v36
	v_add_f32_e32 v11, v11, v12
	v_add_f32_e32 v24, v10, v11
	v_cvt_pk_bf16_f32 v22, v34, v35
	v_cvt_pk_bf16_f32 v23, v36, v37
	s_waitcnt vmcnt(7)
	v_cndmask_b32_e64 v13, v87, 0, s[16:17]
	v_cndmask_b32_e64 v12, v86, 0, s[16:17]
	v_cndmask_b32_e64 v11, v85, 0, s[16:17]
	v_cndmask_b32_e64 v10, v84, 0, s[16:17]
	global_store_dwordx4 v[42:43], v[10:13], off offset:3072
	global_store_dwordx2 v[44:45], v[46:47], off
	global_store_dwordx2 v[44:45], v[48:49], off offset:512
	global_store_dwordx2 v[44:45], v[14:15], off offset:1024
	global_store_dwordx2 v[44:45], v[16:17], off offset:1536
	global_store_dwordx2 v[44:45], v[18:19], off offset:2048
	global_store_dwordx2 v[44:45], v[20:21], off offset:2560
	global_store_dwordx2 v[44:45], v[22:23], off offset:3072
	v_mul_f32_e32 v16, v11, v11
	v_mul_f32_e32 v17, v13, v13
	v_fmac_f32_e32 v16, v10, v10
	v_fmac_f32_e32 v17, v12, v12
	v_cvt_pk_bf16_f32 v14, v10, v11
	v_add_f32_e32 v10, v16, v17
	v_add_f32_e32 v10, v24, v10
	v_cvt_pk_bf16_f32 v15, v12, v13
	global_store_dwordx2 v[44:45], v[14:15], off offset:3584
	s_nop 0
	v_add_f32_dpp v10, v10, v10 quad_perm:[1,0,3,2] row_mask:0xf bank_mask:0xf bound_ctrl:1
	s_nop 1
	v_add_f32_dpp v10, v10, v10 quad_perm:[2,3,0,1] row_mask:0xf bank_mask:0xf bound_ctrl:1
	s_nop 1
	v_add_f32_dpp v10, v10, v10 row_half_mirror row_mask:0xf bank_mask:0xf bound_ctrl:1
	s_nop 1
	v_add_f32_dpp v10, v10, v10 row_mirror row_mask:0xf bank_mask:0xf bound_ctrl:1
	v_mov_b32_e32 v11, v10
	s_nop 1
	v_permlane16_swap_b32 v10, v11
	s_nop 0
	v_add_f32_e32 v10, v10, v11
	v_mov_b32_e32 v11, v10
	s_nop 1
	v_permlane32_swap_b32 v10, v11
	s_and_saveexec_b64 s[16:17], s[4:5]
	s_cbranch_execz .LBB0_15
	v_add_f32_e32 v10, v10, v11
	v_fmamk_f32 v10, v10, 0x3a000000, v9
	v_rsq_f32_e32 v10, v10
	s_add_u32 s18, s0, s22
	s_addc_u32 s19, s1, s23
	global_store_dword v1, v10, s[18:19]
	s_branch .LBB0_15

;     __device__ __forceinline__ void operator()(const f32x4 (&acc)[2][2][4][2], const Unit& u, int wr, int wc, int fr, int fq) const {
;     ...
;         const bool isq = u.pn < 6; const int row0 = u.pm * BM + wr * 64 + fr, ldc = isq ? 1536 : 2048, col0 = (isq ? u.pn : u.pn - 6) * BM + wc * 32 + 8 * fq;
;         bf16_t* base = isq ? OQ : OKV; const float* sq = SSQC + (isq ? 0 : 8);
;         float rr[2][4];
; #pragma unroll
;         for (int ai = 0; ai < 2; ++ai)
; #pragma unroll
;             for (int m = 0; m < 4; ++m) { const f32x4* q = (const f32x4*)(sq + (size_t)(row0 + ai * HALF + m * 16) * 16); const f32x4 a = q[0] + q[1];
;                 rr[ai][m] = __builtin_amdgcn_rsqf(((a[0] + a[1]) + (a[2] + a[3])) * (1.0f / 512.0f) + 1e-6f); }
.LBB0_630:
	s_lshl_b32 s0, s47, 8
	s_lshl_b32 s15, s46, 8
	v_mov_b32_e32 v149, v143
	v_mov_b32_e32 v140, v141
	s_add_i32 s0, s0, s40
	s_add_i32 s20, s15, 0xfffffa00
	s_cmp_lt_i32 s46, 6
	v_add_u32_e32 v154, s0, v140
	s_mov_b32 s0, 0x27200000
	s_cselect_b32 s21, s0, 0x28b00000
	s_movk_i32 s0, 0x800
	s_cselect_b32 s22, 0, 32
	s_cselect_b32 s0, 0x600, s0
	s_cselect_b32 s15, s15, s20
	s_add_u32 s20, s6, s21
	s_addc_u32 s21, s7, 0
	s_add_u32 s22, s38, s22
	v_ashrrev_i32_e32 v155, 31, v154
	s_addc_u32 s23, s39, 0
	v_lshlrev_b64 v[150:151], 6, v[154:155]
	v_lshl_add_u64 v[156:157], s[22:23], 0, v[150:151]
	v_lshlrev_b32_e32 v244, 6, v154
	global_load_dwordx4 v[190:193], v244, s[22:23]
	global_load_dwordx4 v[194:197], v244, s[22:23] offset:16
	v_add_u32_e32 v245, 0x400, v244
	global_load_dwordx4 v[198:201], v245, s[22:23]
	global_load_dwordx4 v[202:205], v245, s[22:23] offset:16
	v_add_u32_e32 v245, 0x800, v244
	global_load_dwordx4 v[206:209], v245, s[22:23]
	global_load_dwordx4 v[210:213], v245, s[22:23] offset:16
	v_add_u32_e32 v245, 0xc00, v244
	global_load_dwordx4 v[214:217], v245, s[22:23]
	global_load_dwordx4 v[218:221], v245, s[22:23] offset:16
	v_add_u32_e32 v245, 0x2000, v244
	global_load_dwordx4 v[222:225], v245, s[22:23]
	global_load_dwordx4 v[226:229], v245, s[22:23] offset:16
	s_nop 0
	v_add_u32_e32 v168, 16, v154
	v_ashrrev_i32_e32 v169, 31, v168
	v_add_u32_e32 v166, 32, v154
	v_ashrrev_i32_e32 v167, 31, v166
	v_add_u32_e32 v164, 48, v154
	v_ashrrev_i32_e32 v165, 31, v164
	s_or_b32 s15, s15, s41
	s_andn2_b64 vcc, exec, s[10:11]
	s_waitcnt vmcnt(8)
	v_pk_add_f32 v[152:153], v[192:193], v[196:197]
	v_pk_add_f32 v[150:151], v[190:191], v[194:195]
	v_add_u32_e32 v245, 0x2400, v244
	global_load_dwordx4 v[190:193], v245, s[22:23]
	global_load_dwordx4 v[194:197], v245, s[22:23] offset:16
	s_nop 0
	v_pk_mov_b32 v[156:157], v[150:151], v[152:153] op_sel:[1,0]
	v_mov_b32_e32 v151, v153
	v_pk_add_f32 v[150:151], v[156:157], v[150:151]
	s_nop 0
	v_add_f32_e32 v140, v150, v151
	v_lshlrev_b64 v[150:151], 6, v[168:169]
	v_lshl_add_u64 v[150:151], s[22:23], 0, v[150:151]
	v_fmamk_f32 v140, v140, 0x3b000000, v230
	v_rsq_f32_e32 v152, v140
	s_waitcnt vmcnt(8)
	v_pk_add_f32 v[150:151], v[200:201], v[204:205]
	v_pk_add_f32 v[156:157], v[198:199], v[202:203]
	v_add_u32_e32 v245, 0x2800, v244
	global_load_dwordx4 v[198:201], v245, s[22:23]
	global_load_dwordx4 v[202:205], v245, s[22:23] offset:16
	v_pk_mul_f32 v[128:129], v[128:129], v[152:153] op_sel_hi:[1,0]
	v_pk_mov_b32 v[158:159], v[156:157], v[150:151] op_sel:[1,0]
	v_mov_b32_e32 v157, v151
	v_pk_add_f32 v[150:151], v[158:159], v[156:157]
	v_lshlrev_b64 v[156:157], 6, v[166:167]
	v_lshl_add_u64 v[160:161], s[22:23], 0, v[156:157]
	s_nop 0
	v_add_f32_e32 v140, v150, v151
	v_fmamk_f32 v140, v140, 0x3b000000, v230
	v_rsq_f32_e32 v150, v140
	v_pk_mul_f32 v[126:127], v[126:127], v[152:153] op_sel_hi:[1,0]
	v_pk_mul_f32 v[120:121], v[120:121], v[152:153] op_sel_hi:[1,0]
	v_pk_mul_f32 v[118:119], v[118:119], v[152:153] op_sel_hi:[1,0]
	s_waitcnt vmcnt(8)
	v_pk_add_f32 v[158:159], v[208:209], v[212:213]
	v_pk_add_f32 v[156:157], v[206:207], v[210:211]
	v_add_u32_e32 v245, 0x2c00, v244
	global_load_dwordx4 v[206:209], v245, s[22:23]
	global_load_dwordx4 v[210:213], v245, s[22:23] offset:16
	s_nop 0
	v_pk_mov_b32 v[160:161], v[156:157], v[158:159] op_sel:[1,0]
	v_mov_b32_e32 v157, v159
	v_pk_add_f32 v[156:157], v[160:161], v[156:157]
	s_nop 0
	v_add_f32_e32 v140, v156, v157
	v_lshlrev_b64 v[156:157], 6, v[164:165]
	v_lshl_add_u64 v[160:161], s[22:23], 0, v[156:157]
	s_nop 0
	v_fmamk_f32 v140, v140, 0x3b000000, v230
	v_rsq_f32_e32 v148, v140
	s_waitcnt vmcnt(8)
	v_pk_add_f32 v[158:159], v[216:217], v[220:221]
	v_pk_add_f32 v[156:157], v[214:215], v[218:219]
	v_add_u32_e32 v162, 0x80, v154
	v_pk_mov_b32 v[160:161], v[156:157], v[158:159] op_sel:[1,0]
	v_mov_b32_e32 v157, v159
	v_pk_add_f32 v[156:157], v[160:161], v[156:157]
	v_ashrrev_i32_e32 v163, 31, v162
	v_add_f32_e32 v140, v156, v157
	v_lshlrev_b64 v[156:157], 6, v[162:163]
	v_lshl_add_u64 v[160:161], s[22:23], 0, v[156:157]
	v_fmamk_f32 v140, v140, 0x3b000000, v230
	v_rsq_f32_e32 v146, v140
	v_pk_mul_f32 v[98:99], v[98:99], v[148:149] op_sel_hi:[1,0]
	v_pk_mul_f32 v[88:89], v[88:89], v[148:149] op_sel_hi:[1,0]
	v_pk_mul_f32 v[86:87], v[86:87], v[148:149] op_sel_hi:[1,0]
	v_pk_mul_f32 v[82:83], v[82:83], v[146:147] op_sel_hi:[1,0]
	v_pk_mul_f32 v[72:73], v[72:73], v[146:147] op_sel_hi:[1,0]
	v_pk_mul_f32 v[70:71], v[70:71], v[146:147] op_sel_hi:[1,0]
	s_waitcnt vmcnt(6)
	v_pk_add_f32 v[158:159], v[224:225], v[228:229]
	v_pk_add_f32 v[156:157], v[222:223], v[226:227]
	s_nop 0
	v_pk_mov_b32 v[160:161], v[156:157], v[158:159] op_sel:[1,0]
	v_mov_b32_e32 v157, v159
	v_pk_add_f32 v[156:157], v[160:161], v[156:157]
	v_add_u32_e32 v160, 0x90, v154
	v_ashrrev_i32_e32 v161, 31, v160
	v_add_f32_e32 v140, v156, v157
	v_lshlrev_b64 v[156:157], 6, v[160:161]
	v_lshl_add_u64 v[182:183], s[22:23], 0, v[156:157]
	s_nop 0
	v_fmamk_f32 v140, v140, 0x3b000000, v230
	v_rsq_f32_e32 v144, v140
	s_waitcnt vmcnt(4)
	v_pk_add_f32 v[158:159], v[192:193], v[196:197]
	v_pk_add_f32 v[156:157], v[190:191], v[194:195]
	v_pk_mul_f32 v[64:65], v[64:65], v[144:145] op_sel_hi:[1,0]
	v_pk_mov_b32 v[182:183], v[156:157], v[158:159] op_sel:[1,0]
	v_mov_b32_e32 v157, v159
	v_add_u32_e32 v158, 0xa0, v154
	v_pk_add_f32 v[156:157], v[182:183], v[156:157]
	v_ashrrev_i32_e32 v159, 31, v158
	v_add_f32_e32 v140, v156, v157
	v_lshlrev_b64 v[156:157], 6, v[158:159]
	v_lshl_add_u64 v[156:157], s[22:23], 0, v[156:157]
	v_fmamk_f32 v140, v140, 0x3b000000, v230
	v_rsq_f32_e32 v142, v140
	v_pk_mul_f32 v[62:63], v[62:63], v[144:145] op_sel_hi:[1,0]
	v_pk_mul_f32 v[56:57], v[56:57], v[144:145] op_sel_hi:[1,0]
	v_pk_mul_f32 v[54:55], v[54:55], v[144:145] op_sel_hi:[1,0]
	v_pk_mul_f32 v[50:51], v[50:51], v[142:143] op_sel_hi:[1,0]
	v_pk_mul_f32 v[40:41], v[40:41], v[142:143] op_sel_hi:[1,0]
	v_pk_mul_f32 v[38:39], v[38:39], v[142:143] op_sel_hi:[1,0]
	s_waitcnt vmcnt(2)
; __device__ __forceinline__ unsigned cvt_pk_bf16(float lo, float hi) { unsigned r; asm volatile("v_cvt_pk_bf16_f32 %0, %1, %2" : "=v"(r) : "v"(lo), "v"(hi)); return r; }
;     __device__ __forceinline__ void operator()(const f32x4 (&acc)[2][2][4][2], const Unit& u, int wr, int wc, int fr, int fq) const {
;     ...
;             for (int m = 0; m < 4; ++m) { const f32x4* q = (const f32x4*)(sq + (size_t)(row0 + ai * HALF + m * 16) * 16); const f32x4 a = q[0] + q[1];
;                 rr[ai][m] = __builtin_amdgcn_rsqf(((a[0] + a[1]) + (a[2] + a[3])) * (1.0f / 512.0f) + 1e-6f); }
; #pragma unroll
;         for (int ai = 0; ai < 2; ++ai)
; #pragma unroll
;             for (int m = 0; m < 4; ++m) { const int row = row0 + ai * HALF + m * 16; bf16_t* p = base + (size_t)row * ldc + col0; const float r = rr[ai][m];
; #pragma unroll
;                 for (int bj = 0; bj < 2; ++bj) { const f32x4 v0 = acc[ai][bj][m][0] * r, v1 = acc[ai][bj][m][1] * r;
;                     u32x4 w; w.x = cvt_pk_bf16(v0[0], v0[1]); w.y = cvt_pk_bf16(v0[2], v0[3]); w.z = cvt_pk_bf16(v1[0], v1[1]); w.w = cvt_pk_bf16(v1[2], v1[3]);
;                     *(u32x4*)(p + bj * HALF) = w; } }
	v_pk_add_f32 v[156:157], v[200:201], v[204:205]
	v_pk_add_f32 v[182:183], v[198:199], v[202:203]
	s_nop 0
	v_pk_mov_b32 v[184:185], v[182:183], v[156:157] op_sel:[1,0]
	v_mov_b32_e32 v183, v157
	v_pk_add_f32 v[156:157], v[184:185], v[182:183]
	s_nop 0
	v_add_f32_e32 v140, v156, v157
	v_add_u32_e32 v156, 0xb0, v154
	v_ashrrev_i32_e32 v157, 31, v156
	v_lshlrev_b64 v[182:183], 6, v[156:157]
	v_lshl_add_u64 v[186:187], s[22:23], 0, v[182:183]
	s_nop 0
	v_fmamk_f32 v140, v140, 0x3b000000, v230
	v_rsq_f32_e32 v140, v140
	s_waitcnt vmcnt(0)
	v_pk_add_f32 v[184:185], v[208:209], v[212:213]
	v_pk_add_f32 v[182:183], v[206:207], v[210:211]
	v_pk_mul_f32 v[34:35], v[34:35], v[140:141] op_sel_hi:[1,0]
	v_pk_mov_b32 v[186:187], v[182:183], v[184:185] op_sel:[1,0]
	v_lshl_add_u32 v184, v149, 3, s15
	v_mov_b32_e32 v183, v185
	v_ashrrev_i32_e32 v185, 31, v184
	v_lshl_add_u64 v[184:185], v[184:185], 1, s[20:21]
	v_mad_i64_i32 v[154:155], s[20:21], s0, v154, 0
	v_pk_add_f32 v[182:183], v[186:187], v[182:183]
	v_lshl_add_u64 v[154:155], v[154:155], 1, v[184:185]
	v_pk_mul_f32 v[186:187], v[124:125], v[152:153] op_sel_hi:[1,0]
	v_pk_mul_f32 v[124:125], v[122:123], v[152:153] op_sel_hi:[1,0]
	v_cvt_pk_bf16_f32 v122, v126, v127
	v_cvt_pk_bf16_f32 v123, v128, v129
	v_add_f32_e32 v151, v182, v183
	v_cvt_pk_bf16_f32 v124, v124, v125
	v_cvt_pk_bf16_f32 v125, v186, v187
	global_store_dwordx4 v[154:155], v[122:125], off
	v_fmamk_f32 v151, v151, 0x3b000000, v230
	v_pk_mul_f32 v[114:115], v[114:115], v[150:151] op_sel_hi:[1,0]
	v_pk_mul_f32 v[122:123], v[112:113], v[152:153] op_sel_hi:[1,0]
	v_pk_mul_f32 v[112:113], v[110:111], v[152:153] op_sel_hi:[1,0]
	v_cvt_pk_bf16_f32 v110, v118, v119
	v_cvt_pk_bf16_f32 v111, v120, v121
	v_pk_mul_f32 v[104:105], v[104:105], v[150:151] op_sel_hi:[1,0]
	v_cvt_pk_bf16_f32 v112, v112, v113
	v_cvt_pk_bf16_f32 v113, v122, v123
	global_store_dwordx4 v[154:155], v[110:113], off offset:256
	v_pk_mul_f32 v[102:103], v[102:103], v[150:151] op_sel_hi:[1,0]
	v_rsq_f32_e32 v182, v151
	v_mad_i64_i32 v[110:111], s[20:21], s0, v168, 0
	v_lshl_add_u64 v[110:111], v[110:111], 1, v[184:185]
	v_pk_mul_f32 v[112:113], v[116:117], v[150:151] op_sel_hi:[1,0]
	v_pk_mul_f32 v[116:117], v[108:109], v[150:151] op_sel_hi:[1,0]
	v_pk_mul_f32 v[108:109], v[106:107], v[150:151] op_sel_hi:[1,0]
	v_cvt_pk_bf16_f32 v106, v114, v115
	v_cvt_pk_bf16_f32 v107, v112, v113
	v_pk_mul_f32 v[24:25], v[24:25], v[140:141] op_sel_hi:[1,0]
	v_cvt_pk_bf16_f32 v108, v108, v109
	v_cvt_pk_bf16_f32 v109, v116, v117
	global_store_dwordx4 v[110:111], v[106:109], off
	v_pk_mul_f32 v[22:23], v[22:23], v[140:141] op_sel_hi:[1,0]
	v_pk_mul_f32 v[18:19], v[18:19], v[182:183] op_sel_hi:[1,0]
	v_pk_mul_f32 v[106:107], v[96:97], v[150:151] op_sel_hi:[1,0]
	v_pk_mul_f32 v[96:97], v[94:95], v[150:151] op_sel_hi:[1,0]
	v_cvt_pk_bf16_f32 v94, v102, v103
	v_cvt_pk_bf16_f32 v95, v104, v105
	v_pk_mul_f32 v[8:9], v[8:9], v[182:183] op_sel_hi:[1,0]
	v_cvt_pk_bf16_f32 v96, v96, v97
	v_cvt_pk_bf16_f32 v97, v106, v107
	global_store_dwordx4 v[110:111], v[94:97], off offset:256
	v_pk_mul_f32 v[6:7], v[6:7], v[182:183] op_sel_hi:[1,0]
	s_nop 0
	v_mad_i64_i32 v[94:95], s[20:21], s0, v166, 0
	v_lshl_add_u64 v[94:95], v[94:95], 1, v[184:185]
	v_pk_mul_f32 v[96:97], v[100:101], v[148:149] op_sel_hi:[1,0]
	v_pk_mul_f32 v[100:101], v[92:93], v[148:149] op_sel_hi:[1,0]
	v_pk_mul_f32 v[92:93], v[90:91], v[148:149] op_sel_hi:[1,0]
	v_cvt_pk_bf16_f32 v90, v98, v99
	v_cvt_pk_bf16_f32 v91, v96, v97
	s_nop 0
	v_cvt_pk_bf16_f32 v92, v92, v93
	v_cvt_pk_bf16_f32 v93, v100, v101
	global_store_dwordx4 v[94:95], v[90:93], off
	s_nop 1
	v_pk_mul_f32 v[90:91], v[80:81], v[148:149] op_sel_hi:[1,0]
	v_pk_mul_f32 v[80:81], v[78:79], v[148:149] op_sel_hi:[1,0]
	v_cvt_pk_bf16_f32 v78, v86, v87
	v_cvt_pk_bf16_f32 v79, v88, v89
	s_nop 0
	v_cvt_pk_bf16_f32 v80, v80, v81
	v_cvt_pk_bf16_f32 v81, v90, v91
	global_store_dwordx4 v[94:95], v[78:81], off offset:256
	s_nop 1
	v_mad_i64_i32 v[78:79], s[20:21], s0, v164, 0
; __device__ __forceinline__ unsigned cvt_pk_bf16(float lo, float hi) { unsigned r; asm volatile("v_cvt_pk_bf16_f32 %0, %1, %2" : "=v"(r) : "v"(lo), "v"(hi)); return r; }
;     __device__ __forceinline__ void operator()(const f32x4 (&acc)[2][2][4][2], const Unit& u, int wr, int wc, int fr, int fq) const {
;     ...
;         for (int ai = 0; ai < 2; ++ai)
; #pragma unroll
;             for (int m = 0; m < 4; ++m) { const int row = row0 + ai * HALF + m * 16; bf16_t* p = base + (size_t)row * ldc + col0; const float r = rr[ai][m];
; #pragma unroll
;                 for (int bj = 0; bj < 2; ++bj) { const f32x4 v0 = acc[ai][bj][m][0] * r, v1 = acc[ai][bj][m][1] * r;
;                     u32x4 w; w.x = cvt_pk_bf16(v0[0], v0[1]); w.y = cvt_pk_bf16(v0[2], v0[3]); w.z = cvt_pk_bf16(v1[0], v1[1]); w.w = cvt_pk_bf16(v1[2], v1[3]);
;                     *(u32x4*)(p + bj * HALF) = w; } }
	v_lshl_add_u64 v[78:79], v[78:79], 1, v[184:185]
	v_pk_mul_f32 v[80:81], v[84:85], v[146:147] op_sel_hi:[1,0]
	v_pk_mul_f32 v[84:85], v[76:77], v[146:147] op_sel_hi:[1,0]
	v_pk_mul_f32 v[76:77], v[74:75], v[146:147] op_sel_hi:[1,0]
	v_cvt_pk_bf16_f32 v74, v82, v83
	v_cvt_pk_bf16_f32 v75, v80, v81
	s_nop 0
	v_cvt_pk_bf16_f32 v76, v76, v77
	v_cvt_pk_bf16_f32 v77, v84, v85
	global_store_dwordx4 v[78:79], v[74:77], off
	s_nop 1
	v_pk_mul_f32 v[74:75], v[68:69], v[146:147] op_sel_hi:[1,0]
	v_pk_mul_f32 v[68:69], v[66:67], v[146:147] op_sel_hi:[1,0]
	v_cvt_pk_bf16_f32 v66, v70, v71
	v_cvt_pk_bf16_f32 v67, v72, v73
	s_nop 0
	v_cvt_pk_bf16_f32 v68, v68, v69
	v_cvt_pk_bf16_f32 v69, v74, v75
	global_store_dwordx4 v[78:79], v[66:69], off offset:256
	s_nop 1
	v_mad_i64_i32 v[66:67], s[20:21], s0, v162, 0
	v_lshl_add_u64 v[66:67], v[66:67], 1, v[184:185]
	v_pk_mul_f32 v[68:69], v[60:61], v[144:145] op_sel_hi:[1,0]
	v_pk_mul_f32 v[60:61], v[58:59], v[144:145] op_sel_hi:[1,0]
	v_cvt_pk_bf16_f32 v58, v62, v63
	v_cvt_pk_bf16_f32 v59, v64, v65
	s_nop 0
	v_cvt_pk_bf16_f32 v60, v60, v61
	v_cvt_pk_bf16_f32 v61, v68, v69
	global_store_dwordx4 v[66:67], v[58:61], off
	s_nop 1
	v_pk_mul_f32 v[58:59], v[48:49], v[144:145] op_sel_hi:[1,0]
	v_pk_mul_f32 v[48:49], v[46:47], v[144:145] op_sel_hi:[1,0]
	v_cvt_pk_bf16_f32 v46, v54, v55
	v_cvt_pk_bf16_f32 v47, v56, v57
	s_nop 0
	v_cvt_pk_bf16_f32 v48, v48, v49
	v_cvt_pk_bf16_f32 v49, v58, v59
	global_store_dwordx4 v[66:67], v[46:49], off offset:256
	s_nop 1
	v_mad_i64_i32 v[46:47], s[20:21], s0, v160, 0
	v_lshl_add_u64 v[46:47], v[46:47], 1, v[184:185]
	v_pk_mul_f32 v[48:49], v[52:53], v[142:143] op_sel_hi:[1,0]
	v_pk_mul_f32 v[52:53], v[44:45], v[142:143] op_sel_hi:[1,0]
	v_pk_mul_f32 v[44:45], v[42:43], v[142:143] op_sel_hi:[1,0]
	v_cvt_pk_bf16_f32 v42, v50, v51
	v_cvt_pk_bf16_f32 v43, v48, v49
	s_nop 0
	v_cvt_pk_bf16_f32 v44, v44, v45
	v_cvt_pk_bf16_f32 v45, v52, v53
	global_store_dwordx4 v[46:47], v[42:45], off
	s_nop 1
	v_pk_mul_f32 v[42:43], v[32:33], v[142:143] op_sel_hi:[1,0]
	v_pk_mul_f32 v[32:33], v[30:31], v[142:143] op_sel_hi:[1,0]
	v_cvt_pk_bf16_f32 v30, v38, v39
	v_cvt_pk_bf16_f32 v31, v40, v41
	s_nop 0
	v_cvt_pk_bf16_f32 v32, v32, v33
	v_cvt_pk_bf16_f32 v33, v42, v43
	global_store_dwordx4 v[46:47], v[30:33], off offset:256
	s_nop 1
	v_mad_i64_i32 v[30:31], s[20:21], s0, v158, 0
	v_lshl_add_u64 v[30:31], v[30:31], 1, v[184:185]
	v_pk_mul_f32 v[32:33], v[36:37], v[140:141] op_sel_hi:[1,0]
	v_pk_mul_f32 v[36:37], v[28:29], v[140:141] op_sel_hi:[1,0]
	v_pk_mul_f32 v[28:29], v[26:27], v[140:141] op_sel_hi:[1,0]
	v_cvt_pk_bf16_f32 v26, v34, v35
	v_cvt_pk_bf16_f32 v27, v32, v33
	s_nop 0
	v_cvt_pk_bf16_f32 v28, v28, v29
	v_cvt_pk_bf16_f32 v29, v36, v37
	global_store_dwordx4 v[30:31], v[26:29], off
	s_nop 1
	v_pk_mul_f32 v[26:27], v[16:17], v[140:141] op_sel_hi:[1,0]
	v_pk_mul_f32 v[16:17], v[14:15], v[140:141] op_sel_hi:[1,0]
	v_cvt_pk_bf16_f32 v14, v22, v23
	v_cvt_pk_bf16_f32 v15, v24, v25
	s_nop 0
	v_cvt_pk_bf16_f32 v16, v16, v17
	v_cvt_pk_bf16_f32 v17, v26, v27
	global_store_dwordx4 v[30:31], v[14:17], off offset:256
	s_nop 1
	v_mad_i64_i32 v[14:15], s[20:21], s0, v156, 0
	v_lshl_add_u64 v[14:15], v[14:15], 1, v[184:185]
	v_pk_mul_f32 v[16:17], v[20:21], v[182:183] op_sel_hi:[1,0]
	v_pk_mul_f32 v[20:21], v[12:13], v[182:183] op_sel_hi:[1,0]
	v_pk_mul_f32 v[12:13], v[10:11], v[182:183] op_sel_hi:[1,0]
	v_cvt_pk_bf16_f32 v10, v18, v19
	v_cvt_pk_bf16_f32 v11, v16, v17
	s_mov_b64 s[20:21], -1
	v_cvt_pk_bf16_f32 v12, v12, v13
	v_cvt_pk_bf16_f32 v13, v20, v21
	global_store_dwordx4 v[14:15], v[10:13], off
	s_nop 1
	v_pk_mul_f32 v[10:11], v[4:5], v[182:183] op_sel_hi:[1,0]
	v_pk_mul_f32 v[4:5], v[2:3], v[182:183] op_sel_hi:[1,0]
	v_cvt_pk_bf16_f32 v2, v6, v7
	v_cvt_pk_bf16_f32 v3, v8, v9
	s_nop 0
	v_cvt_pk_bf16_f32 v4, v4, v5
	v_cvt_pk_bf16_f32 v5, v10, v11
	global_store_dwordx4 v[14:15], v[2:5], off offset:256
	s_cbranch_vccnz .LBB0_615
	s_andn2_b64 vcc, exec, s[8:9]
	s_cbranch_vccnz .LBB0_614
	s_barrier
	s_branch .LBB0_614
